# attn: Q row loads batched per query block and prefetched one block ahead (counted vmcnt), stores switched flat->global
# speedup vs baseline: 1.0078x; 1.0055x over previous
.LBB0_243:
	s_or_b64 exec, exec, s[0:1]
	global_load_dwordx4 v[32:35], v[126:127], off offset:48
	global_load_dwordx4 v[36:39], v[126:127], off offset:32
	global_load_dwordx4 v[40:43], v[126:127], off offset:16
	global_load_dwordx4 v[44:47], v[126:127], off
	s_waitcnt vmcnt(0) lgkmcnt(0)
	v_and_b32_e32 v60, 0xffff0000, v22
	v_lshlrev_b32_e32 v61, 16, v22
	v_and_b32_e32 v64, 0xffff0000, v23
	v_lshlrev_b32_e32 v65, 16, v23
	v_lshlrev_b32_e32 v68, 16, v27
	v_and_b32_e32 v69, 0xffff0000, v27
	v_lshlrev_b32_e32 v72, 16, v26
	v_and_b32_e32 v73, 0xffff0000, v26
	v_lshlrev_b32_e32 v76, 16, v25
	v_and_b32_e32 v77, 0xffff0000, v25
	v_lshlrev_b32_e32 v80, 16, v24
	v_and_b32_e32 v81, 0xffff0000, v24
	v_lshlrev_b32_e32 v90, 16, v29
	v_and_b32_e32 v91, 0xffff0000, v29
	v_lshlrev_b32_e32 v94, 16, v28
	v_and_b32_e32 v95, 0xffff0000, v28
	global_load_dwordx4 v[22:25], v[126:127], off offset:112
	global_load_dwordx4 v[26:29], v[126:127], off offset:96
	global_load_dwordx4 v[48:51], v[126:127], off offset:80
	global_load_dwordx4 v[52:55], v[126:127], off offset:64
	v_pk_mul_f32 v[82:83], v[80:81], v[80:81]
	v_pk_mul_f32 v[78:79], v[76:77], v[76:77]
	v_add_f32_e32 v82, v82, v83
	v_add_f32_e32 v78, v78, v82
	v_pk_mul_f32 v[74:75], v[72:73], v[72:73]
	v_add_f32_e32 v78, v79, v78
	v_add_f32_e32 v74, v74, v78
	v_pk_mul_f32 v[70:71], v[68:69], v[68:69]
	v_add_f32_e32 v74, v75, v74
	v_add_f32_e32 v70, v70, v74
	v_pk_mul_f32 v[96:97], v[94:95], v[94:95]
	v_add_f32_e32 v70, v71, v70
	v_add_f32_e32 v70, v96, v70
	v_pk_mul_f32 v[92:93], v[90:91], v[90:91]
	v_add_f32_e32 v70, v97, v70
	v_lshlrev_b32_e32 v88, 16, v30
	v_and_b32_e32 v89, 0xffff0000, v30
	v_add_f32_e32 v70, v92, v70
	v_lshlrev_b32_e32 v84, 16, v31
	v_and_b32_e32 v85, 0xffff0000, v31
	v_pk_mul_f32 v[30:31], v[88:89], v[88:89]
	v_add_f32_e32 v70, v93, v70
	v_add_f32_e32 v30, v30, v70
	v_pk_mul_f32 v[86:87], v[84:85], v[84:85]
	v_add_f32_e32 v30, v31, v30
	v_lshlrev_b32_e32 v108, 16, v16
	v_and_b32_e32 v109, 0xffff0000, v16
	v_add_f32_e32 v30, v86, v30
	v_lshlrev_b32_e32 v104, 16, v17
	v_and_b32_e32 v105, 0xffff0000, v17
	v_pk_mul_f32 v[16:17], v[108:109], v[108:109]
	v_add_f32_e32 v30, v87, v30
	v_add_f32_e32 v16, v16, v30
	v_pk_mul_f32 v[106:107], v[104:105], v[104:105]
	v_add_f32_e32 v16, v17, v16
	v_lshlrev_b32_e32 v102, 16, v18
	v_and_b32_e32 v103, 0xffff0000, v18
	v_add_f32_e32 v16, v106, v16
	v_lshlrev_b32_e32 v98, 16, v19
	v_and_b32_e32 v99, 0xffff0000, v19
	v_pk_mul_f32 v[18:19], v[102:103], v[102:103]
	v_add_f32_e32 v16, v107, v16
	v_add_f32_e32 v16, v18, v16
	v_pk_mul_f32 v[100:101], v[98:99], v[98:99]
	v_add_f32_e32 v16, v19, v16
	v_lshlrev_b32_e32 v110, 16, v20
	v_and_b32_e32 v111, 0xffff0000, v20
	v_add_f32_e32 v16, v100, v16
	v_and_b32_e32 v56, 0xffff0000, v21
	v_lshlrev_b32_e32 v57, 16, v21
	v_pk_mul_f32 v[20:21], v[110:111], v[110:111]
	v_add_f32_e32 v16, v101, v16
	v_add_f32_e32 v16, v20, v16
	v_pk_mul_f32 v[58:59], v[56:57], v[56:57]
	v_add_f32_e32 v16, v21, v16
	v_add_f32_e32 v16, v59, v16
	v_pk_mul_f32 v[62:63], v[60:61], v[60:61]
	v_add_f32_e32 v16, v58, v16
	v_add_f32_e32 v16, v63, v16
	v_pk_mul_f32 v[66:67], v[64:65], v[64:65]
	v_add_f32_e32 v16, v62, v16
	v_add_f32_e32 v16, v67, v16
	v_add_f32_e32 v16, v66, v16
	ds_bpermute_b32 v17, v139, v16
	s_and_b32 s0, s47, 3
	s_lshl_b32 s5, s0, 9
	v_readlane_b32 s6, v255, 32
	v_readlane_b32 s8, v255, 34
	s_waitcnt lgkmcnt(0)
	v_add_f32_e32 v16, v16, v17
	v_fmamk_f32 v16, v16, 0x3c800000, v195
	v_mul_f32_e32 v17, 0x4f800000, v16
	v_cmp_gt_f32_e32 vcc, s48, v16
	v_readlane_b32 s10, v255, 36
	v_readlane_b32 s12, v255, 38
	v_cndmask_b32_e32 v16, v16, v17, vcc
	v_sqrt_f32_e32 v17, v16
	v_readlane_b32 s14, v255, 40
	v_readlane_b32 s16, v255, 42
	v_readlane_b32 s18, v255, 44
	v_add_u32_e32 v18, -1, v17
	v_fma_f32 v19, -v18, v17, v16
	v_cmp_ge_f32_e64 s[0:1], 0, v19
	v_add_u32_e32 v19, 1, v17
	v_readlane_b32 s20, v255, 46
	v_cndmask_b32_e64 v18, v17, v18, s[0:1]
	v_fma_f32 v17, -v19, v17, v16
	v_cmp_lt_f32_e64 s[0:1], 0, v17
	v_readlane_b32 s22, v255, 48
	v_readlane_b32 s7, v255, 33
	v_cndmask_b32_e64 v17, v18, v19, s[0:1]
	v_mul_f32_e32 v18, 0x37800000, v17
	v_cndmask_b32_e32 v17, v17, v18, vcc
	v_cmp_class_f32_e32 vcc, v16, v197
	v_readlane_b32 s9, v255, 35
	v_readlane_b32 s11, v255, 37
	v_cndmask_b32_e32 v16, v17, v16, vcc
	v_div_scale_f32 v17, s[0:1], v16, v16, 1.0
	v_rcp_f32_e32 v18, v17
	s_add_i32 s0, s46, s5
	s_ashr_i32 s1, s0, 31
	s_lshl_b64 s[44:45], s[0:1], 1
	v_fma_f32 v19, -v17, v18, 1.0
	v_fmac_f32_e32 v18, v19, v18
	v_div_scale_f32 v19, vcc, 1.0, v16, 1.0
	v_mul_f32_e32 v20, v19, v18
	v_fma_f32 v21, -v17, v20, v19
	v_fmac_f32_e32 v20, v21, v18
	v_fma_f32 v17, -v17, v20, v19
	v_div_fmas_f32 v17, v17, v18, v20
	v_div_fixup_f32 v16, v17, v16, 1.0
	v_pk_mul_f32 v[30:31], v[16:17], v[72:73] op_sel_hi:[0,1]
	v_pk_mul_f32 v[20:21], v[16:17], v[76:77] op_sel_hi:[0,1]
	v_pk_mul_f32 v[30:31], v[40:41], v[30:31]
	v_pk_mul_f32 v[40:41], v[16:17], v[68:69] op_sel_hi:[0,1]
	v_pk_mul_f32 v[20:21], v[46:47], v[20:21]
	v_pk_mul_f32 v[40:41], v[42:43], v[40:41]
	v_pk_mul_f32 v[42:43], v[16:17], v[94:95] op_sel_hi:[0,1]
	v_pk_mul_f32 v[46:47], v[16:17], v[102:103] op_sel_hi:[0,1]
	v_pk_mul_f32 v[36:37], v[36:37], v[42:43]
	v_pk_mul_f32 v[42:43], v[16:17], v[90:91] op_sel_hi:[0,1]
	s_waitcnt vmcnt(1)
	v_pk_mul_f32 v[46:47], v[48:49], v[46:47]
	v_pk_mul_f32 v[48:49], v[16:17], v[98:99] op_sel_hi:[0,1]
	v_pk_mul_f32 v[38:39], v[38:39], v[42:43]
	v_pk_mul_f32 v[42:43], v[16:17], v[88:89] op_sel_hi:[0,1]
	v_pk_mul_f32 v[48:49], v[50:51], v[48:49]
	v_pk_mul_f32 v[50:51], v[16:17], v[110:111] op_sel_hi:[0,1]
	v_pk_mul_f32 v[18:19], v[16:17], v[80:81] op_sel_hi:[0,1]
	v_pk_mul_f32 v[32:33], v[32:33], v[42:43]
	v_pk_mul_f32 v[42:43], v[16:17], v[84:85] op_sel_hi:[0,1]
	v_pk_mul_f32 v[26:27], v[26:27], v[50:51]
	v_pk_mul_f32 v[50:51], v[16:17], v[56:57] op_sel_hi:[0,1]
	s_lshl_b32 s0, s4, 3
	v_readlane_b32 s1, v255, 17
	v_pk_mul_f32 v[18:19], v[44:45], v[18:19]
	v_pk_mul_f32 v[34:35], v[34:35], v[42:43]
	v_pk_mul_f32 v[42:43], v[16:17], v[108:109] op_sel_hi:[0,1]
	v_pk_mul_f32 v[44:45], v[16:17], v[104:105] op_sel_hi:[0,1]
	v_pk_mul_f32 v[28:29], v[28:29], v[50:51] op_sel:[0,1] op_sel_hi:[1,0]
	v_pk_mul_f32 v[50:51], v[16:17], v[60:61] op_sel_hi:[0,1]
	v_pk_mul_f32 v[16:17], v[16:17], v[64:65] op_sel_hi:[0,1]
	s_add_i32 s0, s0, s1
	v_pk_mul_f32 v[24:25], v[24:25], v[16:17] op_sel:[0,1] op_sel_hi:[1,0]
	v_cvt_pk_bf16_f32 v16, v18, v19
	v_cvt_pk_bf16_f32 v17, v20, v21
	v_cvt_pk_bf16_f32 v18, v30, v31
	v_cvt_pk_bf16_f32 v19, v40, v41
	s_ashr_i32 s1, s0, 31
	s_waitcnt vmcnt(0)
	v_pk_mul_f32 v[42:43], v[52:53], v[42:43]
	v_pk_mul_f32 v[44:45], v[54:55], v[44:45]
	ds_write_b128 v150, v[16:19]
	v_cvt_pk_bf16_f32 v16, v36, v37
	v_cvt_pk_bf16_f32 v17, v38, v39
	v_cvt_pk_bf16_f32 v18, v32, v33
	v_cvt_pk_bf16_f32 v19, v34, v35
	s_lshl_b64 s[0:1], s[0:1], 2
	v_pk_mul_f32 v[22:23], v[22:23], v[50:51] op_sel:[0,1] op_sel_hi:[1,0]
	ds_write_b128 v150, v[16:19] offset:16
	v_cvt_pk_bf16_f32 v16, v42, v43
	v_cvt_pk_bf16_f32 v17, v44, v45
	v_cvt_pk_bf16_f32 v18, v46, v47
	v_cvt_pk_bf16_f32 v19, v48, v49
	s_add_u32 s0, s38, s0
	v_readlane_b32 s4, v255, 19
	ds_write_b128 v150, v[16:19] offset:32
	v_cvt_pk_bf16_f32 v16, v26, v27
	v_cvt_pk_bf16_f32 v17, v28, v29
	v_cvt_pk_bf16_f32 v18, v22, v23
	v_cvt_pk_bf16_f32 v19, v24, v25
	s_addc_u32 s1, s4, s1
	ds_write_b128 v150, v[16:19] offset:48
	ds_write_b16 v141, v12 offset:36864
	ds_write_b16_d16_hi v141, v12 offset:37392
	ds_write_b16 v142, v13 offset:36864
	ds_write_b16_d16_hi v142, v13 offset:37392
	ds_write_b16 v143, v14 offset:36864
	ds_write_b16_d16_hi v143, v14 offset:37392
	ds_write_b16 v144, v15 offset:36864
	ds_write_b16_d16_hi v144, v15 offset:37392
	ds_write_b16 v145, v4 offset:36864
	ds_write_b16_d16_hi v145, v4 offset:37392
	ds_write_b16 v141, v5 offset:42144
	ds_write_b16_d16_hi v141, v5 offset:42672
	ds_write_b16 v141, v6 offset:43200
	ds_write_b16_d16_hi v141, v6 offset:43728
	ds_write_b16 v141, v7 offset:44256
	ds_write_b16_d16_hi v141, v7 offset:44784
	ds_write_b16 v146, v8 offset:36864
	ds_write_b16_d16_hi v146, v8 offset:37392
	ds_write_b16 v141, v9 offset:46368
	ds_write_b16_d16_hi v141, v9 offset:46896
	ds_write_b16 v141, v10 offset:47424
	ds_write_b16_d16_hi v141, v10 offset:47952
	ds_write_b16 v141, v11 offset:48480
	ds_write_b16_d16_hi v141, v11 offset:49008
	ds_write_b16 v147, v0 offset:36864
	ds_write_b16_d16_hi v147, v0 offset:37392
	ds_write_b16 v141, v1 offset:50592
	ds_write_b16_d16_hi v141, v1 offset:51120
	ds_write_b16 v141, v2 offset:51648
	ds_write_b16_d16_hi v141, v2 offset:52176
	ds_write_b16 v141, v3 offset:52704
	ds_write_b16_d16_hi v141, v3 offset:53232
	s_waitcnt lgkmcnt(0)
	s_barrier
	global_load_dword v0, v161, s[0:1]
	global_load_dwordx4 v[80:83], v[124:125], off
	global_load_dwordx4 v[84:87], v[124:125], off offset:16
	global_load_dwordx4 v[88:91], v[124:125], off offset:64
	global_load_dwordx4 v[92:95], v[124:125], off offset:80
	global_load_dwordx4 v[96:99], v[124:125], off offset:128
	global_load_dwordx4 v[100:103], v[124:125], off offset:144
	global_load_dwordx4 v[104:107], v[124:125], off offset:192
	global_load_dwordx4 v[108:111], v[124:125], off offset:208
	s_ashr_i32 s37, s36, 31
	s_cmp_gt_i32 s36, 0
	v_readlane_b32 s4, v255, 28
	s_cselect_b64 s[42:43], -1, 0
	v_readlane_b32 s5, v255, 29
	v_readlane_b32 s0, v255, 26
	s_and_b64 s[34:35], s[4:5], s[42:43]
	v_readlane_b32 s4, v255, 30
	v_readlane_b32 s1, v255, 27
	v_readlane_b32 s5, v255, 31
	v_readlane_b32 s13, v255, 39
	v_readlane_b32 s15, v255, 41
	v_readlane_b32 s17, v255, 43
	v_readlane_b32 s19, v255, 45
	v_readlane_b32 s21, v255, 47
	v_readlane_b32 s23, v255, 49
	s_and_b64 s[0:1], s[0:1], s[42:43]
	s_and_b64 s[4:5], s[4:5], s[42:43]
	s_and_b64 s[6:7], s[6:7], s[42:43]
	s_and_b64 s[8:9], s[8:9], s[42:43]
	s_and_b64 s[10:11], s[10:11], s[42:43]
	s_and_b64 s[12:13], s[12:13], s[42:43]
	s_and_b64 s[14:15], s[14:15], s[42:43]
	s_and_b64 s[16:17], s[16:17], s[42:43]
	s_and_b64 s[18:19], s[18:19], s[42:43]
	s_and_b64 s[20:21], s[20:21], s[42:43]
	s_and_b64 s[22:23], s[22:23], s[42:43]
	s_and_b64 s[24:25], s[58:59], s[42:43]
	s_and_b64 s[26:27], s[60:61], s[42:43]
	s_and_b64 s[28:29], s[62:63], s[42:43]
	s_and_b64 s[30:31], s[64:65], s[42:43]
	s_lshl_b64 s[36:37], s[36:37], 19
	s_add_u32 s36, s36, s44
	s_addc_u32 s37, s37, s45
	v_lshl_add_u64 v[134:135], v[128:129], 0, s[36:37]
	v_lshl_add_u64 v[136:137], v[130:131], 0, s[36:37]
	s_mov_b64 s[44:45], 0
	v_mov_b32_e32 v152, v149
	v_mov_b32_e32 v151, v148
	s_waitcnt vmcnt(8)
	v_mul_f32_e32 v133, 0x3fb8aa3b, v0
	v_lshl_add_u64 v[216:217], v[134:135], 0, s[44:45]
	s_nop 0
	v_add_co_u32_e32 v216, vcc, 0x1b400000, v216
	s_nop 1
	v_addc_co_u32_e32 v217, vcc, 0, v217, vcc
	global_load_dwordx4 v[200:203], v[216:217], off
	global_load_dwordx4 v[204:207], v[216:217], off offset:32
	global_load_dwordx4 v[208:211], v[216:217], off offset:64
	global_load_dwordx4 v[212:215], v[216:217], off offset:96
	s_waitcnt vmcnt(0)
.LBB0_244:
	v_lshl_add_u64 v[0:1], v[134:135], 0, s[44:45]
	v_add_co_u32_e32 v4, vcc, 0x1b400000, v0
	v_add_u32_e32 v153, 0x1200, v152
	s_nop 0
	v_addc_co_u32_e32 v5, vcc, 0, v1, vcc
	s_nop 0
	s_waitcnt vmcnt(11) lgkmcnt(0)
	v_mov_b32_e32 v0, v200
	v_mov_b32_e32 v1, v201
	v_mov_b32_e32 v2, v202
	v_mov_b32_e32 v3, v203
	v_lshlrev_b32_e32 v6, 16, v0
	v_and_b32_e32 v7, 0xffff0000, v0
	v_lshlrev_b32_e32 v8, 16, v1
	v_and_b32_e32 v9, 0xffff0000, v1
	v_lshlrev_b32_e32 v10, 16, v2
	v_and_b32_e32 v11, 0xffff0000, v2
	v_lshlrev_b32_e32 v12, 16, v3
	v_and_b32_e32 v13, 0xffff0000, v3
	s_nop 0
	v_mul_f32_e32 v16, v7, v7
	v_fmac_f32_e32 v16, v6, v6
	v_fmac_f32_e32 v16, v8, v8
	v_fmac_f32_e32 v16, v9, v9
	v_fmac_f32_e32 v16, v10, v10
	v_fmac_f32_e32 v16, v11, v11
	v_fmac_f32_e32 v16, v12, v12
	v_fmac_f32_e32 v16, v13, v13
	s_waitcnt vmcnt(10) lgkmcnt(0)
	v_mov_b32_e32 v0, v204
	v_mov_b32_e32 v1, v205
	v_mov_b32_e32 v2, v206
	v_mov_b32_e32 v3, v207
	v_lshlrev_b32_e32 v14, 16, v0
	v_and_b32_e32 v15, 0xffff0000, v0
	v_lshlrev_b32_e32 v20, 16, v1
	v_and_b32_e32 v21, 0xffff0000, v1
	v_lshlrev_b32_e32 v22, 16, v2
	v_and_b32_e32 v23, 0xffff0000, v2
	v_lshlrev_b32_e32 v24, 16, v3
	v_and_b32_e32 v25, 0xffff0000, v3
	s_nop 0
	v_fmac_f32_e32 v16, v14, v14
	v_fmac_f32_e32 v16, v15, v15
	v_fmac_f32_e32 v16, v20, v20
	v_fmac_f32_e32 v16, v21, v21
	v_fmac_f32_e32 v16, v22, v22
	v_fmac_f32_e32 v16, v23, v23
	v_fmac_f32_e32 v16, v24, v24
	v_fmac_f32_e32 v16, v25, v25
	s_waitcnt vmcnt(9) lgkmcnt(0)
	v_mov_b32_e32 v0, v208
	v_mov_b32_e32 v1, v209
	v_mov_b32_e32 v2, v210
	v_mov_b32_e32 v3, v211
	v_lshlrev_b32_e32 v26, 16, v0
	v_and_b32_e32 v27, 0xffff0000, v0
	v_lshlrev_b32_e32 v28, 16, v1
	v_and_b32_e32 v29, 0xffff0000, v1
	v_lshlrev_b32_e32 v30, 16, v2
	v_and_b32_e32 v31, 0xffff0000, v2
	v_lshlrev_b32_e32 v32, 16, v3
	v_and_b32_e32 v33, 0xffff0000, v3
	s_nop 0
	v_fmac_f32_e32 v16, v26, v26
	v_fmac_f32_e32 v16, v27, v27
	v_fmac_f32_e32 v16, v28, v28
	v_fmac_f32_e32 v16, v29, v29
	v_fmac_f32_e32 v16, v30, v30
	v_fmac_f32_e32 v16, v31, v31
	v_fmac_f32_e32 v16, v32, v32
	v_fmac_f32_e32 v16, v33, v33
	s_waitcnt vmcnt(8) lgkmcnt(0)
	v_mov_b32_e32 v0, v212
	v_mov_b32_e32 v1, v213
	v_mov_b32_e32 v2, v214
	v_mov_b32_e32 v3, v215
	s_cmp_eq_u32 s44, 0x60000
	s_cbranch_scc1 .Lmy_attn_nopf
	v_lshl_add_u64 v[216:217], v[134:135], 0, s[44:45]
	s_nop 0
	v_add_co_u32_e32 v216, vcc, 0x1b420000, v216
	s_nop 1
	v_addc_co_u32_e32 v217, vcc, 0, v217, vcc
	global_load_dwordx4 v[200:203], v[216:217], off
	global_load_dwordx4 v[204:207], v[216:217], off offset:32
	global_load_dwordx4 v[208:211], v[216:217], off offset:64
	global_load_dwordx4 v[212:215], v[216:217], off offset:96
.Lmy_attn_nopf:
	v_lshlrev_b32_e32 v4, 16, v0
	v_and_b32_e32 v5, 0xffff0000, v0
	v_fmac_f32_e32 v16, v4, v4
	v_lshlrev_b32_e32 v34, 16, v1
	v_fmac_f32_e32 v16, v5, v5
	v_and_b32_e32 v35, 0xffff0000, v1
	v_fmac_f32_e32 v16, v34, v34
	v_lshlrev_b32_e32 v36, 16, v2
	v_fmac_f32_e32 v16, v35, v35
	v_and_b32_e32 v37, 0xffff0000, v2
	v_fmac_f32_e32 v16, v36, v36
	v_and_b32_e32 v0, 0xffff0000, v3
	v_lshlrev_b32_e32 v1, 16, v3
	v_fmac_f32_e32 v16, v37, v37
	v_pk_mul_f32 v[2:3], v[0:1], v[0:1]
	s_nop 0
	v_add_f32_e32 v3, v3, v16
	v_add_f32_e32 v2, v2, v3
	ds_bpermute_b32 v3, v140, v2
	s_waitcnt lgkmcnt(0)
	v_add_f32_e32 v2, v2, v3
	v_fmamk_f32 v2, v2, 0x3c800000, v195
	v_cmp_gt_f32_e64 s[36:37], s48, v2
	v_mul_f32_e32 v3, 0x4f800000, v2
	s_nop 0
	v_cndmask_b32_e64 v2, v2, v3, s[36:37]
	v_sqrt_f32_e32 v3, v2
	s_nop 0
	v_add_u32_e32 v16, -1, v3
	v_fma_f32 v17, -v16, v3, v2
	v_cmp_ge_f32_e32 vcc, 0, v17
	v_add_u32_e32 v17, 1, v3
	s_nop 0
	v_cndmask_b32_e32 v16, v3, v16, vcc
	v_fma_f32 v3, -v17, v3, v2
	v_cmp_lt_f32_e32 vcc, 0, v3
	s_nop 1
	v_cndmask_b32_e32 v3, v16, v17, vcc
	v_mul_f32_e32 v16, 0x37800000, v3
	v_cndmask_b32_e64 v3, v3, v16, s[36:37]
	v_cmp_class_f32_e32 vcc, v2, v197
	s_nop 1
	v_cndmask_b32_e32 v2, v3, v2, vcc
	v_div_scale_f32 v3, s[36:37], v2, v2, 1.0
	v_rcp_f32_e32 v16, v3
	s_add_i32 s36, s55, 1
	s_cmp_gt_u32 s55, 2
	s_mov_b32 s37, 0x1d400000
	v_fma_f32 v17, -v3, v16, 1.0
	v_fmac_f32_e32 v16, v17, v16
	v_div_scale_f32 v17, vcc, 1.0, v2, 1.0
	v_mul_f32_e32 v18, v17, v16
	v_fma_f32 v19, -v3, v18, v17
	v_fmac_f32_e32 v18, v19, v16
	v_fma_f32 v3, -v3, v18, v17
	v_div_fmas_f32 v3, v3, v16, v18
	v_div_fixup_f32 v2, v3, v2, 1.0
	v_mul_f32_e32 v2, 0x3e000000, v2
	v_mul_f32_e32 v2, 0x3fb8aa3b, v2
	v_mul_f32_e32 v3, v2, v6
	v_mul_f32_e32 v3, v80, v3
	v_mul_f32_e32 v6, v2, v7
	v_mul_f32_e32 v7, v2, v8
	v_mul_f32_e32 v8, v2, v9
	v_mul_f32_e32 v6, v81, v6
	v_mul_f32_e32 v7, v82, v7
	v_mul_f32_e32 v8, v83, v8
	v_cvt_pk_bf16_f32 v16, v3, v6
	v_mul_f32_e32 v3, v2, v14
	v_mul_f32_e32 v9, v2, v10
	v_mul_f32_e32 v10, v2, v11
	v_mul_f32_e32 v11, v2, v12
	v_mul_f32_e32 v12, v2, v13
	v_cvt_pk_bf16_f32 v17, v7, v8
	v_mul_f32_e32 v3, v88, v3
	v_mul_f32_e32 v6, v2, v15
	v_mul_f32_e32 v7, v2, v20
	v_mul_f32_e32 v8, v2, v21
	v_mul_f32_e32 v9, v84, v9
	v_mul_f32_e32 v10, v85, v10
	v_mul_f32_e32 v11, v86, v11
	v_mul_f32_e32 v12, v87, v12
	v_cvt_pk_bf16_f32 v18, v9, v10
	v_cvt_pk_bf16_f32 v19, v11, v12
	v_mul_f32_e32 v6, v89, v6
	v_mul_f32_e32 v7, v90, v7
	v_mul_f32_e32 v8, v91, v8
	v_cvt_pk_bf16_f32 v112, v3, v6
	v_mul_f32_e32 v3, v2, v26
	v_mul_f32_e32 v9, v2, v22
	v_mul_f32_e32 v10, v2, v23
	v_mul_f32_e32 v11, v2, v24
	v_mul_f32_e32 v12, v2, v25
	v_cvt_pk_bf16_f32 v113, v7, v8
	v_mul_f32_e32 v3, v96, v3
	v_mul_f32_e32 v6, v2, v27
	v_mul_f32_e32 v7, v2, v28
	v_mul_f32_e32 v8, v2, v29
	v_mul_f32_e32 v9, v92, v9
	v_mul_f32_e32 v10, v93, v10
	v_mul_f32_e32 v11, v94, v11
	v_mul_f32_e32 v12, v95, v12
	v_cvt_pk_bf16_f32 v114, v9, v10
	v_cvt_pk_bf16_f32 v115, v11, v12
	v_mul_f32_e32 v6, v97, v6
	v_mul_f32_e32 v7, v98, v7
	v_mul_f32_e32 v8, v99, v8
	v_cvt_pk_bf16_f32 v116, v3, v6
	v_mul_f32_e32 v3, v2, v4
	v_mul_f32_e32 v1, v2, v1
	v_mul_f32_e32 v0, v2, v0
	v_mul_f32_e32 v9, v2, v30
	v_mul_f32_e32 v10, v2, v31
	v_mul_f32_e32 v11, v2, v32
	v_mul_f32_e32 v12, v2, v33
	v_cvt_pk_bf16_f32 v117, v7, v8
	v_mul_f32_e32 v3, v104, v3
	v_mul_f32_e32 v4, v2, v5
	v_mul_f32_e32 v5, v2, v34
	v_mul_f32_e32 v6, v2, v35
	v_mul_f32_e32 v7, v2, v36
	v_mul_f32_e32 v8, v2, v37
	v_mul_f32_e32 v1, v110, v1
	v_mul_f32_e32 v0, v111, v0
	v_mul_f32_e32 v9, v100, v9
	v_mul_f32_e32 v10, v101, v10
	v_mul_f32_e32 v11, v102, v11
	v_mul_f32_e32 v12, v103, v12
	v_cvt_pk_bf16_f32 v118, v9, v10
	v_cvt_pk_bf16_f32 v119, v11, v12
	v_mul_f32_e32 v4, v105, v4
	v_mul_f32_e32 v5, v106, v5
	v_mul_f32_e32 v6, v107, v6
	v_mul_f32_e32 v7, v108, v7
	v_mul_f32_e32 v8, v109, v8
	v_cvt_pk_bf16_f32 v120, v3, v4
	v_cvt_pk_bf16_f32 v121, v5, v6
	v_cvt_pk_bf16_f32 v122, v7, v8
	v_cvt_pk_bf16_f32 v123, v1, v0
	ds_read_b128 v[0:3], v152
	ds_read_b128 v[20:23], v152 offset:32
	s_waitcnt lgkmcnt(1)
	v_mfma_f32_32x32x16_bf16 v[0:15], v[0:3], v[16:19], 0
	ds_read_b128 v[154:157], v152 offset:18464
	s_cselect_b64 vcc, -1, 0
	s_or_b64 vcc, s[42:43], vcc
	s_cmp_gt_u32 s55, 1
	s_mov_b32 s55, s36
	s_waitcnt lgkmcnt(1)
	v_mfma_f32_32x32x16_bf16 v[0:15], v[20:23], v[112:115], v[0:15]
	ds_read_b128 v[20:23], v152 offset:64
	s_waitcnt lgkmcnt(0)
	v_mfma_f32_32x32x16_bf16 v[0:15], v[20:23], v[116:119], v[0:15]
	ds_read_b128 v[20:23], v152 offset:96
	s_waitcnt lgkmcnt(0)
	v_mfma_f32_32x32x16_bf16 v[0:15], v[20:23], v[120:123], v[0:15]
	ds_read_b128 v[20:23], v152 offset:4608
	s_waitcnt lgkmcnt(0)
	v_mfma_f32_32x32x16_bf16 v[64:79], v[20:23], v[16:19], 0
	ds_read_b128 v[20:23], v152 offset:4640
	s_nop 7
	v_cndmask_b32_e64 v0, v237, v0, s[0:1]
	v_cndmask_b32_e64 v1, v237, v1, s[34:35]
	v_cndmask_b32_e64 v2, v237, v2, s[4:5]
	v_cndmask_b32_e64 v3, v237, v3, s[6:7]
	v_cndmask_b32_e64 v4, v237, v4, s[8:9]
	v_cndmask_b32_e64 v5, v237, v5, s[10:11]
	s_waitcnt lgkmcnt(0)
	v_mfma_f32_32x32x16_bf16 v[64:79], v[20:23], v[112:115], v[64:79]
	ds_read_b128 v[20:23], v152 offset:4672
	v_cndmask_b32_e64 v6, v237, v6, s[12:13]
	v_cndmask_b32_e64 v7, v237, v7, s[14:15]
	v_cndmask_b32_e64 v8, v237, v8, s[16:17]
	v_cndmask_b32_e64 v9, v237, v9, s[18:19]
	v_cndmask_b32_e64 v10, v237, v10, s[20:21]
	v_cndmask_b32_e64 v11, v237, v11, s[22:23]
	s_waitcnt lgkmcnt(0)
	v_mfma_f32_32x32x16_bf16 v[64:79], v[20:23], v[116:119], v[64:79]
	ds_read_b128 v[20:23], v152 offset:4704
	v_cndmask_b32_e64 v12, v237, v12, s[24:25]
	v_cndmask_b32_e64 v13, v237, v13, s[26:27]
	v_cndmask_b32_e64 v14, v237, v14, s[28:29]
	v_cndmask_b32_e64 v15, v237, v15, s[30:31]
	s_waitcnt lgkmcnt(0)
	v_mfma_f32_32x32x16_bf16 v[64:79], v[20:23], v[120:123], v[64:79]
	ds_read_b128 v[20:23], v152 offset:9216
	s_waitcnt lgkmcnt(0)
	v_mfma_f32_32x32x16_bf16 v[48:63], v[20:23], v[16:19], 0
	ds_read_b128 v[20:23], v152 offset:9248
	s_nop 7
	v_cndmask_b32_e32 v64, v237, v64, vcc
	v_cndmask_b32_e32 v65, v237, v65, vcc
	v_cndmask_b32_e32 v66, v237, v66, vcc
	v_cndmask_b32_e32 v67, v237, v67, vcc
	v_cndmask_b32_e32 v68, v237, v68, vcc
	v_cndmask_b32_e32 v69, v237, v69, vcc
	s_waitcnt lgkmcnt(0)
	v_mfma_f32_32x32x16_bf16 v[48:63], v[20:23], v[112:115], v[48:63]
	ds_read_b128 v[20:23], v152 offset:9280
	v_cndmask_b32_e32 v70, v237, v70, vcc
	v_cndmask_b32_e32 v71, v237, v71, vcc
	v_cndmask_b32_e32 v72, v237, v72, vcc
	v_cndmask_b32_e32 v73, v237, v73, vcc
	v_cndmask_b32_e32 v74, v237, v74, vcc
	v_cndmask_b32_e32 v75, v237, v75, vcc
	s_waitcnt lgkmcnt(0)
	v_mfma_f32_32x32x16_bf16 v[48:63], v[20:23], v[116:119], v[48:63]
	ds_read_b128 v[20:23], v152 offset:9312
	v_cndmask_b32_e32 v76, v237, v76, vcc
	v_cndmask_b32_e32 v77, v237, v77, vcc
	v_cndmask_b32_e32 v78, v237, v78, vcc
	v_cndmask_b32_e32 v79, v237, v79, vcc
	s_cselect_b64 vcc, -1, 0
	s_or_b64 vcc, s[42:43], vcc
	s_waitcnt lgkmcnt(0)
	v_mfma_f32_32x32x16_bf16 v[48:63], v[20:23], v[120:123], v[48:63]
	ds_read_b128 v[20:23], v152 offset:13824
	s_cmp_lg_u32 s44, 0
	s_waitcnt lgkmcnt(0)
	v_mfma_f32_32x32x16_bf16 v[32:47], v[20:23], v[16:19], 0
	ds_read_b128 v[20:23], v152 offset:13856
	s_nop 6
	v_cndmask_b32_e32 v49, v237, v49, vcc
	v_cndmask_b32_e32 v50, v237, v50, vcc
	v_cndmask_b32_e32 v51, v237, v51, vcc
	v_cndmask_b32_e32 v52, v237, v52, vcc
	v_cndmask_b32_e32 v53, v237, v53, vcc
	v_cndmask_b32_e32 v54, v237, v54, vcc
	s_waitcnt lgkmcnt(0)
	v_mfma_f32_32x32x16_bf16 v[32:47], v[20:23], v[112:115], v[32:47]
	ds_read_b128 v[20:23], v152 offset:13888
	v_cndmask_b32_e32 v55, v237, v55, vcc
	v_cndmask_b32_e32 v57, v237, v57, vcc
	v_cndmask_b32_e32 v58, v237, v58, vcc
	v_cndmask_b32_e32 v59, v237, v59, vcc
	v_cndmask_b32_e32 v60, v237, v60, vcc
	v_cndmask_b32_e32 v61, v237, v61, vcc
	s_waitcnt lgkmcnt(0)
	v_mfma_f32_32x32x16_bf16 v[32:47], v[20:23], v[116:119], v[32:47]
	ds_read_b128 v[20:23], v152 offset:13920
	v_cndmask_b32_e32 v62, v237, v62, vcc
	v_cndmask_b32_e32 v63, v237, v63, vcc
	s_waitcnt lgkmcnt(0)
	v_mfma_f32_32x32x16_bf16 v[32:47], v[20:23], v[120:123], v[32:47]
	ds_read_b128 v[20:23], v152 offset:18432
	s_waitcnt lgkmcnt(0)
	v_mfma_f32_32x32x16_bf16 v[16:31], v[20:23], v[16:19], 0
	v_mfma_f32_32x32x16_bf16 v[16:31], v[154:157], v[112:115], v[16:31]
	ds_read_b128 v[112:115], v152 offset:18496
	s_waitcnt lgkmcnt(0)
	v_mfma_f32_32x32x16_bf16 v[16:31], v[112:115], v[116:119], v[16:31]
	ds_read_b128 v[112:115], v152 offset:18528
	s_waitcnt lgkmcnt(0)
	v_mfma_f32_32x32x16_bf16 v[16:31], v[112:115], v[120:123], v[16:31]
	v_max3_f32 v112, v133, v0, v1
	v_max3_f32 v112, v112, v2, v3
	v_max3_f32 v112, v112, v4, v5
	v_max3_f32 v112, v112, v6, v7
	v_max3_f32 v112, v112, v8, v9
	v_max3_f32 v112, v112, v10, v11
	v_max3_f32 v112, v112, v12, v13
	v_max3_f32 v112, v112, v14, v15
	v_max3_f32 v112, v112, v64, v65
	v_max3_f32 v112, v112, v66, v67
	v_max3_f32 v112, v112, v68, v69
	v_max3_f32 v112, v112, v70, v71
	v_max3_f32 v112, v112, v72, v73
	v_max3_f32 v112, v112, v74, v75
	v_max3_f32 v112, v112, v76, v77
	v_max3_f32 v112, v112, v78, v79
	v_cndmask_b32_e32 v113, v237, v48, vcc
	v_max3_f32 v48, v112, v113, v49
	v_max3_f32 v48, v48, v50, v51
	v_max3_f32 v48, v48, v52, v53
	v_max3_f32 v48, v48, v54, v55
	v_cndmask_b32_e32 v112, v237, v56, vcc
	v_max3_f32 v48, v48, v112, v57
	v_max3_f32 v48, v48, v58, v59
	s_cselect_b64 vcc, -1, 0
	v_max3_f32 v48, v48, v60, v61
	s_or_b64 vcc, s[42:43], vcc
	v_max3_f32 v48, v48, v62, v63
	v_cndmask_b32_e32 v114, v237, v32, vcc
	v_cndmask_b32_e32 v115, v237, v33, vcc
	v_max3_f32 v32, v48, v114, v115
	v_cndmask_b32_e32 v116, v237, v34, vcc
	v_cndmask_b32_e32 v117, v237, v35, vcc
	v_max3_f32 v32, v32, v116, v117
	v_cndmask_b32_e32 v118, v237, v36, vcc
	v_cndmask_b32_e32 v119, v237, v37, vcc
	v_max3_f32 v32, v32, v118, v119
	v_cndmask_b32_e32 v120, v237, v38, vcc
	v_cndmask_b32_e32 v121, v237, v39, vcc
	v_max3_f32 v32, v32, v120, v121
	v_cndmask_b32_e32 v122, v237, v40, vcc
	v_cndmask_b32_e32 v123, v237, v41, vcc
	v_max3_f32 v32, v32, v122, v123
	v_cndmask_b32_e32 v152, v237, v42, vcc
	v_cndmask_b32_e32 v154, v237, v43, vcc
	v_max3_f32 v32, v32, v152, v154
	v_cndmask_b32_e32 v155, v237, v44, vcc
	v_cndmask_b32_e32 v156, v237, v45, vcc
	v_max3_f32 v32, v32, v155, v156
	v_cndmask_b32_e32 v157, v237, v46, vcc
	v_cndmask_b32_e32 v158, v237, v47, vcc
	v_max3_f32 v32, v32, v157, v158
	v_cndmask_b32_e64 v16, v237, v16, s[66:67]
	v_cndmask_b32_e64 v17, v237, v17, s[68:69]
	v_max3_f32 v32, v32, v16, v17
	v_cndmask_b32_e64 v18, v237, v18, s[70:71]
	v_cndmask_b32_e64 v19, v237, v19, s[72:73]
	v_max3_f32 v32, v32, v18, v19
	v_cndmask_b32_e64 v20, v237, v20, s[74:75]
	v_cndmask_b32_e64 v21, v237, v21, s[76:77]
	v_max3_f32 v32, v32, v20, v21
	v_cndmask_b32_e64 v22, v237, v22, s[78:79]
	v_cndmask_b32_e64 v23, v237, v23, s[80:81]
	v_max3_f32 v32, v32, v22, v23
	v_cndmask_b32_e64 v24, v237, v24, s[82:83]
	v_cndmask_b32_e64 v25, v237, v25, s[84:85]
	v_max3_f32 v32, v32, v24, v25
	v_cndmask_b32_e64 v26, v237, v26, s[86:87]
	v_cndmask_b32_e64 v27, v237, v27, s[88:89]
	v_max3_f32 v32, v32, v26, v27
	v_cndmask_b32_e64 v28, v237, v28, s[90:91]
	v_cndmask_b32_e64 v29, v237, v29, s[92:93]
	v_max3_f32 v32, v32, v28, v29
	v_cndmask_b32_e64 v30, v237, v30, s[94:95]
	v_cndmask_b32_e64 v31, v237, v31, s[96:97]
	v_max3_f32 v32, v32, v30, v31
	ds_bpermute_b32 v33, v140, v32
	s_waitcnt lgkmcnt(0)
	v_max_f32_e32 v33, v33, v33
	v_max_f32_e32 v159, v32, v33
	v_sub_f32_e32 v0, v0, v159
	v_exp_f32_e32 v0, v0
	v_sub_f32_e32 v1, v1, v159
	v_exp_f32_e32 v1, v1
	v_sub_f32_e32 v2, v2, v159
	v_exp_f32_e32 v2, v2
	v_sub_f32_e32 v3, v3, v159
	v_exp_f32_e32 v3, v3
	v_sub_f32_e32 v4, v4, v159
	v_add_f32_e32 v32, 0, v0
	v_exp_f32_e32 v4, v4
	v_sub_f32_e32 v5, v5, v159
	v_add_f32_e32 v32, v1, v32
	v_exp_f32_e32 v5, v5
	v_sub_f32_e32 v6, v6, v159
	v_add_f32_e32 v32, v2, v32
	v_exp_f32_e32 v6, v6
	v_sub_f32_e32 v7, v7, v159
	v_add_f32_e32 v32, v3, v32
	v_exp_f32_e32 v7, v7
	v_sub_f32_e32 v8, v8, v159
	v_add_f32_e32 v32, v4, v32
	v_exp_f32_e32 v160, v8
	v_sub_f32_e32 v9, v9, v159
	v_add_f32_e32 v32, v5, v32
	v_exp_f32_e32 v170, v9
	v_sub_f32_e32 v9, v10, v159
	v_add_f32_e32 v32, v6, v32
	v_exp_f32_e32 v171, v9
	v_sub_f32_e32 v9, v11, v159
	v_add_f32_e32 v32, v7, v32
	v_exp_f32_e32 v172, v9
	v_sub_f32_e32 v9, v12, v159
	v_add_f32_e32 v8, v160, v32
	v_exp_f32_e32 v173, v9
	v_sub_f32_e32 v9, v13, v159
	v_add_f32_e32 v8, v170, v8
	v_exp_f32_e32 v174, v9
	v_sub_f32_e32 v9, v14, v159
	v_add_f32_e32 v8, v171, v8
	v_exp_f32_e32 v175, v9
	v_sub_f32_e32 v9, v15, v159
	v_add_f32_e32 v8, v172, v8
	v_exp_f32_e32 v176, v9
	v_sub_f32_e32 v9, v64, v159
	v_add_f32_e32 v8, v173, v8
	v_exp_f32_e32 v32, v9
	v_sub_f32_e32 v9, v65, v159
	v_add_f32_e32 v8, v174, v8
	v_exp_f32_e32 v33, v9
	v_sub_f32_e32 v9, v66, v159
	v_add_f32_e32 v8, v175, v8
	v_exp_f32_e32 v34, v9
	v_sub_f32_e32 v9, v67, v159
	v_add_f32_e32 v8, v176, v8
	v_exp_f32_e32 v35, v9
	v_sub_f32_e32 v9, v68, v159
	v_add_f32_e32 v8, v32, v8
	v_exp_f32_e32 v36, v9
	v_sub_f32_e32 v9, v69, v159
	v_add_f32_e32 v8, v33, v8
	v_exp_f32_e32 v37, v9
	v_sub_f32_e32 v9, v70, v159
	v_add_f32_e32 v8, v34, v8
	v_exp_f32_e32 v38, v9
	v_sub_f32_e32 v9, v71, v159
	v_add_f32_e32 v8, v35, v8
	v_exp_f32_e32 v40, v9
	v_sub_f32_e32 v9, v72, v159
	v_add_f32_e32 v8, v36, v8
	v_exp_f32_e32 v39, v9
	v_sub_f32_e32 v9, v73, v159
	v_add_f32_e32 v8, v37, v8
	v_exp_f32_e32 v41, v9
	v_sub_f32_e32 v9, v74, v159
	v_add_f32_e32 v8, v38, v8
	v_exp_f32_e32 v42, v9
	v_sub_f32_e32 v9, v75, v159
	v_add_f32_e32 v8, v40, v8
	v_exp_f32_e32 v43, v9
	v_sub_f32_e32 v9, v76, v159
	v_add_f32_e32 v8, v39, v8
	v_exp_f32_e32 v44, v9
	v_sub_f32_e32 v9, v77, v159
	v_add_f32_e32 v8, v41, v8
	v_exp_f32_e32 v45, v9
	v_sub_f32_e32 v9, v78, v159
	v_add_f32_e32 v8, v42, v8
	v_exp_f32_e32 v46, v9
	v_sub_f32_e32 v9, v79, v159
	v_add_f32_e32 v8, v43, v8
	v_exp_f32_e32 v48, v9
	v_sub_f32_e32 v9, v113, v159
	v_add_f32_e32 v8, v44, v8
	v_exp_f32_e32 v47, v9
	v_sub_f32_e32 v9, v49, v159
	v_add_f32_e32 v8, v45, v8
	v_exp_f32_e32 v49, v9
	v_sub_f32_e32 v9, v50, v159
	v_add_f32_e32 v8, v46, v8
	v_exp_f32_e32 v50, v9
	v_sub_f32_e32 v9, v51, v159
	v_add_f32_e32 v8, v48, v8
	v_exp_f32_e32 v51, v9
	v_sub_f32_e32 v9, v52, v159
	v_add_f32_e32 v8, v47, v8
	v_exp_f32_e32 v52, v9
	v_sub_f32_e32 v9, v53, v159
	v_add_f32_e32 v8, v49, v8
	v_exp_f32_e32 v53, v9
	v_sub_f32_e32 v9, v54, v159
	v_add_f32_e32 v8, v50, v8
	v_exp_f32_e32 v54, v9
	v_sub_f32_e32 v9, v55, v159
	v_add_f32_e32 v8, v51, v8
	v_exp_f32_e32 v56, v9
	v_sub_f32_e32 v9, v112, v159
	v_add_f32_e32 v8, v52, v8
	v_exp_f32_e32 v55, v9
	v_sub_f32_e32 v9, v57, v159
	v_add_f32_e32 v8, v53, v8
	v_exp_f32_e32 v57, v9
	v_sub_f32_e32 v9, v58, v159
	v_add_f32_e32 v8, v54, v8
	v_exp_f32_e32 v58, v9
	v_sub_f32_e32 v9, v59, v159
	v_add_f32_e32 v8, v56, v8
	v_exp_f32_e32 v59, v9
	v_sub_f32_e32 v9, v60, v159
	v_add_f32_e32 v8, v55, v8
	v_exp_f32_e32 v60, v9
	v_sub_f32_e32 v9, v61, v159
	v_add_f32_e32 v8, v57, v8
	v_exp_f32_e32 v61, v9
	v_sub_f32_e32 v9, v62, v159
	v_add_f32_e32 v8, v58, v8
	v_exp_f32_e32 v62, v9
	v_sub_f32_e32 v9, v63, v159
	v_add_f32_e32 v8, v59, v8
	v_exp_f32_e32 v64, v9
	v_sub_f32_e32 v9, v114, v159
	v_add_f32_e32 v8, v60, v8
	v_exp_f32_e32 v63, v9
	v_sub_f32_e32 v9, v115, v159
	v_add_f32_e32 v8, v61, v8
	v_exp_f32_e32 v65, v9
	v_sub_f32_e32 v9, v116, v159
	v_add_f32_e32 v8, v62, v8
	v_exp_f32_e32 v66, v9
	v_sub_f32_e32 v9, v117, v159
	v_add_f32_e32 v8, v64, v8
	v_exp_f32_e32 v67, v9
	v_sub_f32_e32 v9, v118, v159
	v_add_f32_e32 v8, v63, v8
	v_exp_f32_e32 v68, v9
	v_sub_f32_e32 v9, v119, v159
	v_add_f32_e32 v8, v65, v8
	v_exp_f32_e32 v69, v9
	v_sub_f32_e32 v9, v120, v159
	v_add_f32_e32 v8, v66, v8
	v_exp_f32_e32 v70, v9
	v_sub_f32_e32 v9, v121, v159
	v_add_f32_e32 v8, v67, v8
	v_exp_f32_e32 v72, v9
	v_sub_f32_e32 v9, v122, v159
	v_add_f32_e32 v8, v68, v8
	v_exp_f32_e32 v71, v9
	v_sub_f32_e32 v9, v123, v159
	v_add_f32_e32 v8, v69, v8
	v_exp_f32_e32 v73, v9
	v_sub_f32_e32 v9, v152, v159
	v_add_f32_e32 v8, v70, v8
	v_exp_f32_e32 v74, v9
	v_sub_f32_e32 v9, v154, v159
	v_add_f32_e32 v8, v72, v8
	v_exp_f32_e32 v75, v9
	v_sub_f32_e32 v9, v155, v159
	v_add_f32_e32 v8, v71, v8
	v_exp_f32_e32 v76, v9
	v_sub_f32_e32 v9, v156, v159
	v_add_f32_e32 v8, v73, v8
	v_exp_f32_e32 v77, v9
	v_sub_f32_e32 v9, v157, v159
	v_add_f32_e32 v8, v74, v8
	v_exp_f32_e32 v78, v9
	v_sub_f32_e32 v9, v158, v159
	v_add_f32_e32 v8, v75, v8
	v_exp_f32_e32 v112, v9
	v_sub_f32_e32 v9, v16, v159
	v_add_f32_e32 v8, v76, v8
	v_exp_f32_e32 v79, v9
	v_sub_f32_e32 v9, v17, v159
	v_add_f32_e32 v8, v77, v8
	v_exp_f32_e32 v113, v9
	v_sub_f32_e32 v9, v18, v159
	v_add_f32_e32 v8, v78, v8
	v_exp_f32_e32 v114, v9
	v_sub_f32_e32 v9, v19, v159
	v_add_f32_e32 v8, v112, v8
	v_exp_f32_e32 v115, v9
	v_sub_f32_e32 v9, v20, v159
	v_add_f32_e32 v8, v79, v8
	v_exp_f32_e32 v116, v9
	v_sub_f32_e32 v9, v21, v159
	v_add_f32_e32 v8, v113, v8
	v_exp_f32_e32 v117, v9
	v_sub_f32_e32 v9, v22, v159
	v_add_f32_e32 v8, v114, v8
	v_exp_f32_e32 v118, v9
	v_sub_f32_e32 v9, v23, v159
	v_add_f32_e32 v8, v115, v8
	v_exp_f32_e32 v120, v9
	v_sub_f32_e32 v9, v24, v159
	v_add_f32_e32 v8, v116, v8
	v_exp_f32_e32 v119, v9
	v_sub_f32_e32 v9, v25, v159
	v_add_f32_e32 v8, v117, v8
	v_exp_f32_e32 v121, v9
	v_sub_f32_e32 v9, v26, v159
	v_add_f32_e32 v8, v118, v8
	v_exp_f32_e32 v122, v9
	v_sub_f32_e32 v9, v27, v159
	v_add_f32_e32 v8, v120, v8
	v_exp_f32_e32 v123, v9
	v_sub_f32_e32 v9, v28, v159
	v_add_f32_e32 v8, v119, v8
	v_exp_f32_e32 v152, v9
	v_sub_f32_e32 v9, v29, v159
	v_add_f32_e32 v8, v121, v8
	v_exp_f32_e32 v154, v9
	v_sub_f32_e32 v9, v30, v159
	v_add_f32_e32 v8, v122, v8
	v_exp_f32_e32 v155, v9
	v_sub_f32_e32 v9, v31, v159
	v_add_f32_e32 v8, v123, v8
	v_exp_f32_e32 v157, v9
	v_add_f32_e32 v8, v152, v8
	v_add_f32_e32 v8, v154, v8
	v_add_f32_e32 v8, v155, v8
	v_add_f32_e32 v8, v157, v8
	ds_bpermute_b32 v9, v140, v8
	v_sub_f32_e32 v10, v133, v159
	v_exp_f32_e32 v156, v10
	v_cvt_pk_bf16_f32 v0, v0, v1
	v_cvt_pk_bf16_f32 v1, v2, v3
	s_waitcnt lgkmcnt(0)
	v_add_f32_e32 v158, v8, v9
	v_cvt_pk_bf16_f32 v2, v4, v5
	v_cvt_pk_bf16_f32 v3, v6, v7
	ds_read_b128 v[4:7], v151
	ds_read_b128 v[8:11], v151 offset:16896
	s_waitcnt lgkmcnt(1)
	v_mfma_f32_32x32x16_bf16 v[16:31], v[4:7], v[0:3], 0
	v_cvt_pk_bf16_f32 v170, v160, v170
	v_cvt_pk_bf16_f32 v171, v171, v172
	v_cvt_pk_bf16_f32 v172, v173, v174
	v_cvt_pk_bf16_f32 v173, v175, v176
	ds_read_b128 v[174:177], v151 offset:32
	ds_read_b128 v[178:181], v151 offset:16928
	v_cvt_pk_bf16_f32 v32, v32, v33
	v_cvt_pk_bf16_f32 v33, v34, v35
	s_waitcnt lgkmcnt(2)
	v_mfma_f32_32x32x16_bf16 v[0:15], v[8:11], v[0:3], 0
	v_cvt_pk_bf16_f32 v34, v36, v37
	v_cvt_pk_bf16_f32 v35, v38, v40
	v_add_u32_e32 v159, 64, v151
	s_waitcnt lgkmcnt(1)
	v_mfma_f32_32x32x16_bf16 v[16:31], v[174:177], v[170:173], v[16:31]
	s_waitcnt lgkmcnt(0)
	v_mfma_f32_32x32x16_bf16 v[0:15], v[178:181], v[170:173], v[0:15]
	ds_read_b128 v[170:173], v151 offset:64
	ds_read_b128 v[174:177], v151 offset:16960
	s_waitcnt lgkmcnt(1)
	v_mfma_f32_32x32x16_bf16 v[16:31], v[170:173], v[32:35], v[16:31]
	s_waitcnt lgkmcnt(0)
	v_mfma_f32_32x32x16_bf16 v[0:15], v[174:177], v[32:35], v[0:15]
	v_cvt_pk_bf16_f32 v32, v39, v41
	v_cvt_pk_bf16_f32 v33, v42, v43
	v_cvt_pk_bf16_f32 v34, v44, v45
	v_cvt_pk_bf16_f32 v35, v46, v48
	ds_read_b128 v[36:39], v151 offset:96
	ds_read_b128 v[40:43], v151 offset:16992
	s_waitcnt lgkmcnt(1)
	v_mfma_f32_32x32x16_bf16 v[16:31], v[36:39], v[32:35], v[16:31]
	s_waitcnt lgkmcnt(0)
	v_mfma_f32_32x32x16_bf16 v[0:15], v[40:43], v[32:35], v[0:15]
	v_cvt_pk_bf16_f32 v32, v47, v49
	v_cvt_pk_bf16_f32 v33, v50, v51
	v_cvt_pk_bf16_f32 v34, v52, v53
	v_cvt_pk_bf16_f32 v35, v54, v56
	ds_read_b128 v[36:39], v151 offset:128
	ds_read_b128 v[40:43], v151 offset:17024
	s_waitcnt lgkmcnt(1)
	v_mfma_f32_32x32x16_bf16 v[16:31], v[36:39], v[32:35], v[16:31]
	s_waitcnt lgkmcnt(0)
	v_mfma_f32_32x32x16_bf16 v[0:15], v[40:43], v[32:35], v[0:15]
	v_cvt_pk_bf16_f32 v32, v55, v57
	v_cvt_pk_bf16_f32 v33, v58, v59
	v_cvt_pk_bf16_f32 v34, v60, v61
	v_cvt_pk_bf16_f32 v35, v62, v64
	ds_read_b128 v[36:39], v151 offset:160
	ds_read_b128 v[40:43], v151 offset:17056
	s_waitcnt lgkmcnt(1)
	v_mfma_f32_32x32x16_bf16 v[16:31], v[36:39], v[32:35], v[16:31]
	s_waitcnt lgkmcnt(0)
	v_mfma_f32_32x32x16_bf16 v[0:15], v[40:43], v[32:35], v[0:15]
	v_cvt_pk_bf16_f32 v32, v63, v65
	v_cvt_pk_bf16_f32 v33, v66, v67
	v_cvt_pk_bf16_f32 v34, v68, v69
	v_cvt_pk_bf16_f32 v35, v70, v72
	ds_read_b128 v[36:39], v151 offset:192
	ds_read_b128 v[40:43], v151 offset:17088
	s_waitcnt lgkmcnt(1)
	v_mfma_f32_32x32x16_bf16 v[16:31], v[36:39], v[32:35], v[16:31]
	s_waitcnt lgkmcnt(0)
	v_mfma_f32_32x32x16_bf16 v[0:15], v[40:43], v[32:35], v[0:15]
	v_cvt_pk_bf16_f32 v32, v71, v73
	v_cvt_pk_bf16_f32 v33, v74, v75
	v_cvt_pk_bf16_f32 v34, v76, v77
	v_cvt_pk_bf16_f32 v35, v78, v112
	ds_read_b128 v[36:39], v151 offset:224
	ds_read_b128 v[40:43], v151 offset:17120
	s_waitcnt lgkmcnt(1)
	v_mfma_f32_32x32x16_bf16 v[16:31], v[36:39], v[32:35], v[16:31]
	s_waitcnt lgkmcnt(0)
	v_mfma_f32_32x32x16_bf16 v[0:15], v[40:43], v[32:35], v[0:15]
	v_cvt_pk_bf16_f32 v32, v79, v113
	v_cvt_pk_bf16_f32 v33, v114, v115
	v_cvt_pk_bf16_f32 v34, v116, v117
	v_cvt_pk_bf16_f32 v35, v118, v120
	ds_read_b128 v[36:39], v151 offset:256
	ds_read_b128 v[40:43], v151 offset:17152
	s_waitcnt lgkmcnt(1)
	v_mfma_f32_32x32x16_bf16 v[16:31], v[36:39], v[32:35], v[16:31]
	s_waitcnt lgkmcnt(0)
	v_mfma_f32_32x32x16_bf16 v[0:15], v[40:43], v[32:35], v[0:15]
	v_cvt_pk_bf16_f32 v32, v119, v121
	v_cvt_pk_bf16_f32 v33, v122, v123
	v_cvt_pk_bf16_f32 v34, v152, v154
	v_cvt_pk_bf16_f32 v35, v155, v157
	ds_read_b128 v[36:39], v151 offset:288
	ds_read_b128 v[40:43], v151 offset:17184
	v_mov_b32_e32 v152, v153
	v_mov_b32_e32 v151, v159
	s_waitcnt lgkmcnt(1)
	v_mfma_f32_32x32x16_bf16 v[16:31], v[36:39], v[32:35], v[16:31]
	s_waitcnt lgkmcnt(0)
	v_mfma_f32_32x32x16_bf16 v[0:15], v[40:43], v[32:35], v[0:15]
	v_add_f32_e32 v32, v156, v158
	v_div_scale_f32 v33, vcc, v32, v32, 1.0
	v_rcp_f32_e32 v34, v33
	s_nop 0
	v_fma_f32 v35, -v33, v34, 1.0
	v_fmac_f32_e32 v34, v35, v34
	v_div_scale_f32 v35, vcc, 1.0, v32, 1.0
	v_mul_f32_e32 v36, v35, v34
	v_fma_f32 v37, -v33, v36, v35
	v_fmac_f32_e32 v36, v37, v34
	v_fma_f32 v33, -v33, v36, v35
	v_div_fmas_f32 v33, v33, v34, v36
	v_div_fixup_f32 v32, v33, v32, 1.0
	v_lshl_add_u64 v[34:35], v[136:137], 0, s[44:45]
	v_pk_mul_f32 v[16:17], v[16:17], v[32:33] op_sel_hi:[1,0]
	v_pk_mul_f32 v[18:19], v[18:19], v[32:33] op_sel_hi:[1,0]
	v_cvt_pk_bf16_f32 v16, v16, v17
	v_cvt_pk_bf16_f32 v17, v18, v19
	v_add_co_u32_e32 v18, vcc, s37, v34
	v_pk_mul_f32 v[0:1], v[0:1], v[32:33] op_sel_hi:[1,0]
	v_pk_mul_f32 v[2:3], v[2:3], v[32:33] op_sel_hi:[1,0]
	v_addc_co_u32_e32 v19, vcc, 0, v35, vcc
	v_cvt_pk_bf16_f32 v0, v0, v1
	v_cvt_pk_bf16_f32 v1, v2, v3
	global_store_dwordx2 v[18:19], v[0:1], off offset:64
	v_pk_mul_f32 v[0:1], v[20:21], v[32:33] op_sel_hi:[1,0]
	v_pk_mul_f32 v[2:3], v[22:23], v[32:33] op_sel_hi:[1,0]
	v_cvt_pk_bf16_f32 v0, v0, v1
	v_cvt_pk_bf16_f32 v1, v2, v3
	global_store_dwordx2 v[18:19], v[0:1], off offset:16
	v_pk_mul_f32 v[0:1], v[4:5], v[32:33] op_sel_hi:[1,0]
	v_pk_mul_f32 v[2:3], v[6:7], v[32:33] op_sel_hi:[1,0]
	v_cvt_pk_bf16_f32 v0, v0, v1
	v_cvt_pk_bf16_f32 v1, v2, v3
	global_store_dwordx2 v[18:19], v[0:1], off offset:80
	v_pk_mul_f32 v[0:1], v[24:25], v[32:33] op_sel_hi:[1,0]
	v_pk_mul_f32 v[2:3], v[26:27], v[32:33] op_sel_hi:[1,0]
	v_cvt_pk_bf16_f32 v0, v0, v1
	v_cvt_pk_bf16_f32 v1, v2, v3
	global_store_dwordx2 v[18:19], v[0:1], off offset:32
	v_pk_mul_f32 v[0:1], v[8:9], v[32:33] op_sel_hi:[1,0]
	v_pk_mul_f32 v[2:3], v[10:11], v[32:33] op_sel_hi:[1,0]
	v_cvt_pk_bf16_f32 v0, v0, v1
	v_cvt_pk_bf16_f32 v1, v2, v3
	global_store_dwordx2 v[18:19], v[0:1], off offset:96
	v_pk_mul_f32 v[0:1], v[28:29], v[32:33] op_sel_hi:[1,0]
	v_pk_mul_f32 v[2:3], v[30:31], v[32:33] op_sel_hi:[1,0]
	v_cvt_pk_bf16_f32 v0, v0, v1
	v_cvt_pk_bf16_f32 v1, v2, v3
	s_add_u32 s44, s44, 0x20000
	global_store_dwordx2 v[18:19], v[0:1], off offset:48
	v_pk_mul_f32 v[0:1], v[12:13], v[32:33] op_sel_hi:[1,0]
	v_pk_mul_f32 v[2:3], v[14:15], v[32:33] op_sel_hi:[1,0]
	s_addc_u32 s45, s45, 0
	v_cvt_pk_bf16_f32 v0, v0, v1
	v_cvt_pk_bf16_f32 v1, v2, v3
	s_cmp_lg_u32 s44, 0x80000
	global_store_dwordx2 v[18:19], v[16:17], off
	global_store_dwordx2 v[18:19], v[0:1], off offset:112
	s_cbranch_scc1 .LBB0_244
	s_add_i32 s54, s54, s56
	s_add_i32 s47, s47, s56
	s_cmpk_gt_i32 s54, 0xff
	s_waitcnt lgkmcnt(0)
	s_barrier
	s_cbranch_scc0 .LBB0_241
